# FFN-up conv/SiLU epilogue rewritten by hand: each thread owns 4 consecutive rows x 8 columns, the 6 source rows are read and widened once (12 LDS reads + 96 unpack ops per pass instead of 24 + 192), w
# speedup vs baseline: 1.0200x; 1.0109x over previous
; #define GAS __attribute__((address_space(1)))
; DI float bflo(unsigned w) { return __uint_as_float(w << 16); }
;     ...
;       const int j8 = (tid2 & 7) * 8;
;       const int ja0 = (nt * 2 + p) * 64, ja = ja0 + j8;
;       f32x4 wa[4][2], wg[4][2];
; #pragma unroll
;       for (int hh = 0; hh < 2; ++hh) {
;         wa[0][hh] = *(const GAS f32x4*)(cw + ja + 4 * hh); wa[1][hh] = *(const GAS f32x4*)(cw + 5632 + ja + 4 * hh); wa[2][hh] = *(const GAS f32x4*)(cw + 11264 + ja + 4 * hh); wa[3][hh] = *(const GAS f32x4*)(cb + ja + 4 * hh);
;         wg[0][hh] = *(const GAS f32x4*)(cw + 2816 + ja + 4 * hh); wg[1][hh] = *(const GAS f32x4*)(cw + 5632 + 2816 + ja + 4 * hh); wg[2][hh] = *(const GAS f32x4*)(cw + 11264 + 2816 + ja + 4 * hh); wg[3][hh] = *(const GAS f32x4*)(cb + 2816 + ja + 4 * hh);
;       }
; #pragma unroll 1
;       for (int i = 0; i < 4; ++i) {
;         const int r = (tid2 + 256 * i) >> 3;
;         const bool top = (r == 0), bot = (r == 127);
;         if ((top && !first) || (bot && !last)) continue;
;         const char* base = smem + r * 528 + (p * 128 + j8) * 2;
;         const u32x4 zz = {0u, 0u, 0u, 0u};
;         const u32x4 pa = top ? zz : *(const u32x4*)(base - 528), ca = *(const u32x4*)base, na = bot ? zz : *(const u32x4*)(base + 528);
;         const u32x4 pg = top ? zz : *(const u32x4*)(base - 528 + 128), cg = *(const u32x4*)(base + 128), ng = bot ? zz : *(const u32x4*)(base + 528 + 128);
;         unsigned resw[4];
; #pragma unroll
;         for (int q = 0; q < 4; ++q) {
;           const int hh = q >> 1, e0 = (q & 1) * 2;
;           const float ua0 = wa[0][hh][e0] * bflo(pa[q]) + wa[1][hh][e0] * bflo(ca[q]) + wa[2][hh][e0] * bflo(na[q]) + wa[3][hh][e0];
;           const float ua1 = wa[0][hh][e0 + 1] * bfhi(pa[q]) + wa[1][hh][e0 + 1] * bfhi(ca[q]) + wa[2][hh][e0 + 1] * bfhi(na[q]) + wa[3][hh][e0 + 1];
;           const float ug0 = wg[0][hh][e0] * bflo(pg[q]) + wg[1][hh][e0] * bflo(cg[q]) + wg[2][hh][e0] * bflo(ng[q]) + wg[3][hh][e0];
;           const float ug1 = wg[0][hh][e0 + 1] * bfhi(pg[q]) + wg[1][hh][e0 + 1] * bfhi(cg[q]) + wg[2][hh][e0 + 1] * bfhi(ng[q]) + wg[3][hh][e0 + 1];
;           resw[q] = pk2(siluf(ug0) * ua0, siluf(ug1) * ua1);
;         }
;         u32x4 w; w.x = resw[0]; w.y = resw[1]; w.z = resw[2]; w.w = resw[3];
;         __builtin_nontemporal_store(w, (GAS u32x4*)(ea.out + (size_t)(m0 + r) * 2816 + ja0 + j8));
.LBB0_275:
	s_lshl_b32 s10, s40, 6
	s_xor_b64 s[22:23], s[28:29], -1
	s_or_b32 s28, s10, s47
	v_or_b32_e32 v2, s28, v96
	v_ashrrev_i32_e32 v3, 31, v2
	v_lshlrev_b64 v[2:3], 2, v[2:3]
	v_lshl_add_u64 v[6:7], s[12:13], 0, v[2:3]
	v_lshl_add_u64 v[14:15], s[52:53], 0, v[2:3]
	v_lshl_add_u64 v[22:23], s[56:57], 0, v[2:3]
	v_lshl_add_u64 v[30:31], s[16:17], 0, v[2:3]
	v_lshl_add_u64 v[38:39], s[58:59], 0, v[2:3]
	v_lshl_add_u64 v[46:47], s[60:61], 0, v[2:3]
	v_lshl_add_u64 v[54:55], s[62:63], 0, v[2:3]
	v_lshl_add_u64 v[62:63], s[64:65], 0, v[2:3]
	global_load_dwordx4 v[2:5], v[6:7], off
	s_nop 0
	global_load_dwordx4 v[6:9], v[6:7], off offset:16
	s_nop 0
	global_load_dwordx4 v[10:13], v[14:15], off
	s_nop 0
	global_load_dwordx4 v[14:17], v[14:15], off offset:16
	s_nop 0
	global_load_dwordx4 v[18:21], v[22:23], off
	s_nop 0
	global_load_dwordx4 v[22:25], v[22:23], off offset:16
	s_nop 0
	global_load_dwordx4 v[26:29], v[30:31], off
	s_nop 0
	global_load_dwordx4 v[30:33], v[30:31], off offset:16
	s_nop 0
	global_load_dwordx4 v[34:37], v[38:39], off
	s_nop 0
	global_load_dwordx4 v[38:41], v[38:39], off offset:16
	s_nop 0
	global_load_dwordx4 v[42:45], v[46:47], off
	s_nop 0
	global_load_dwordx4 v[46:49], v[46:47], off offset:16
	s_nop 0
	global_load_dwordx4 v[50:53], v[54:55], off
	s_nop 0
	global_load_dwordx4 v[54:57], v[54:55], off offset:16
	s_nop 0
	global_load_dwordx4 v[58:61], v[62:63], off
	s_nop 0
	global_load_dwordx4 v[62:65], v[62:63], off offset:16
	s_ashr_i32 s29, s28, 31
	v_lshl_add_u32 v0, s40, 8, v97
	v_lshl_add_u64 v[92:93], s[28:29], 1, v[90:91]
	s_branch .LBB0_278
.LBB0_278:
	v_lshrrev_b32_e32 v98, 3, v189
	v_lshlrev_b32_e32 v98, 2, v98
	v_mad_u64_u32 v[94:95], s[74:75], v98, s55, v[0:1]
	v_cmp_ne_u32_e32 vcc, 0, v98
	v_add_u32_e32 v99, 0xfffffdf0, v94
	s_movk_i32 s10, 0x7c
	v_cmp_eq_u32_e64 s[74:75], 0, v98
	v_cndmask_b32_e32 v99, v94, v99, vcc
	v_cmp_eq_u32_e64 s[40:41], s10, v98
	ds_read_b128 v[138:141], v99
	ds_read_b128 v[142:145], v99 offset:128
	ds_read_b128 v[146:149], v94 offset:0
	ds_read_b128 v[150:153], v94 offset:128
	ds_read_b128 v[154:157], v94 offset:528
	ds_read_b128 v[158:161], v94 offset:656
	ds_read_b128 v[162:165], v94 offset:1056
	ds_read_b128 v[166:169], v94 offset:1184
	ds_read_b128 v[170:173], v94 offset:1584
	ds_read_b128 v[174:177], v94 offset:1712
	ds_read_b128 v[178:181], v94 offset:2112
	ds_read_b128 v[182:185], v94 offset:2240
	v_add_u32_e32 v88, s46, v98
	s_movk_i32 s10, 0x1600
	v_mad_i64_i32 v[88:89], s[28:29], v88, s10, v[92:93]
	s_mov_b32 s11, 0
	s_waitcnt vmcnt(0)
	s_waitcnt lgkmcnt(10)
	s_and_b64 s[28:29], exec, s[74:75]
	s_cbranch_scc0 .Lmy_e1_top
	s_mov_b64 vcc, exec
	s_mov_b64 exec, s[28:29]
	v_mov_b32_e32 v138, 0
	v_mov_b32_e32 v139, 0
	v_mov_b32_e32 v140, 0
	v_mov_b32_e32 v141, 0
	v_mov_b32_e32 v142, 0
	v_mov_b32_e32 v143, 0
	v_mov_b32_e32 v144, 0
	v_mov_b32_e32 v145, 0
	s_mov_b64 exec, vcc
.Lmy_e1_top:
	v_lshlrev_b32_e32 v66, 16, v138
	v_and_b32_e32 v67, 0xffff0000, v138
	v_lshlrev_b32_e32 v68, 16, v139
	v_and_b32_e32 v69, 0xffff0000, v139
	v_lshlrev_b32_e32 v70, 16, v140
	v_and_b32_e32 v71, 0xffff0000, v140
	v_lshlrev_b32_e32 v72, 16, v141
	v_and_b32_e32 v73, 0xffff0000, v141
	v_lshlrev_b32_e32 v74, 16, v142
	v_and_b32_e32 v75, 0xffff0000, v142
	v_lshlrev_b32_e32 v76, 16, v143
	v_and_b32_e32 v77, 0xffff0000, v143
	v_lshlrev_b32_e32 v78, 16, v144
	v_and_b32_e32 v79, 0xffff0000, v144
	v_lshlrev_b32_e32 v80, 16, v145
	v_and_b32_e32 v81, 0xffff0000, v145
	s_waitcnt lgkmcnt(8)
	v_lshlrev_b32_e32 v104, 16, v146
	v_and_b32_e32 v105, 0xffff0000, v146
	v_lshlrev_b32_e32 v106, 16, v147
	v_and_b32_e32 v107, 0xffff0000, v147
	v_lshlrev_b32_e32 v108, 16, v148
	v_and_b32_e32 v109, 0xffff0000, v148
	v_lshlrev_b32_e32 v110, 16, v149
	v_and_b32_e32 v111, 0xffff0000, v149
	v_lshlrev_b32_e32 v112, 16, v150
	v_and_b32_e32 v113, 0xffff0000, v150
	v_lshlrev_b32_e32 v114, 16, v151
	v_and_b32_e32 v115, 0xffff0000, v151
	v_lshlrev_b32_e32 v116, 16, v152
	v_and_b32_e32 v117, 0xffff0000, v152
	v_lshlrev_b32_e32 v118, 16, v153
	v_and_b32_e32 v119, 0xffff0000, v153
	s_waitcnt lgkmcnt(6)
	v_lshlrev_b32_e32 v120, 16, v154
	v_and_b32_e32 v121, 0xffff0000, v154
	v_lshlrev_b32_e32 v122, 16, v155
	v_and_b32_e32 v123, 0xffff0000, v155
	v_lshlrev_b32_e32 v124, 16, v156
	v_and_b32_e32 v125, 0xffff0000, v156
	v_lshlrev_b32_e32 v126, 16, v157
	v_and_b32_e32 v127, 0xffff0000, v157
	v_lshlrev_b32_e32 v128, 16, v158
	v_and_b32_e32 v129, 0xffff0000, v158
	v_lshlrev_b32_e32 v82, 16, v159
	v_and_b32_e32 v83, 0xffff0000, v159
	v_lshlrev_b32_e32 v84, 16, v160
	v_and_b32_e32 v85, 0xffff0000, v160
	v_lshlrev_b32_e32 v86, 16, v161
	v_and_b32_e32 v87, 0xffff0000, v161
	v_mul_f32_e32 v138, v10, v104
	v_mul_f32_e32 v139, v11, v105
	v_mul_f32_e32 v140, v12, v106
	v_mul_f32_e32 v141, v13, v107
	v_fma_f32 v66, v2, v66, v138
	v_fma_f32 v67, v3, v67, v139
	v_fma_f32 v68, v4, v68, v140
	v_fma_f32 v69, v5, v69, v141
	v_fma_f32 v66, v18, v120, v66
	v_fma_f32 v67, v19, v121, v67
	v_fma_f32 v68, v20, v122, v68
	v_fma_f32 v69, v21, v123, v69
	v_add_f32_e32 v66, v26, v66
	v_add_f32_e32 v67, v27, v67
	v_add_f32_e32 v68, v28, v68
	v_add_f32_e32 v69, v29, v69
	v_mul_f32_e32 v138, v14, v108
	v_mul_f32_e32 v139, v15, v109
	v_mul_f32_e32 v140, v16, v110
	v_mul_f32_e32 v141, v17, v111
	v_fma_f32 v70, v6, v70, v138
	v_fma_f32 v71, v7, v71, v139
	v_fma_f32 v72, v8, v72, v140
	v_fma_f32 v73, v9, v73, v141
	v_fma_f32 v70, v22, v124, v70
	v_fma_f32 v71, v23, v125, v71
	v_fma_f32 v72, v24, v126, v72
	v_fma_f32 v73, v25, v127, v73
	v_add_f32_e32 v70, v30, v70
	v_add_f32_e32 v71, v31, v71
	v_add_f32_e32 v72, v32, v72
	v_add_f32_e32 v73, v33, v73
; #define GAS __attribute__((address_space(1)))
; DI unsigned pk2(float a, float b) { f32x2 v = {a, b}; bf2_t r = __builtin_convertvector(v, bf2_t); return __builtin_bit_cast(unsigned, r); }
; DI float bflo(unsigned w) { return __uint_as_float(w << 16); }
; DI float bfhi(unsigned w) { return __uint_as_float(w & 0xffff0000u); }
; DI float siluf(float v) { return v * __builtin_amdgcn_rcpf(1.f + __builtin_amdgcn_exp2f(-1.4426950408889634f * v)); }
;     ...
;         for (int q = 0; q < 4; ++q) {
;           const int hh = q >> 1, e0 = (q & 1) * 2;
;           const float ua0 = wa[0][hh][e0] * bflo(pa[q]) + wa[1][hh][e0] * bflo(ca[q]) + wa[2][hh][e0] * bflo(na[q]) + wa[3][hh][e0];
;           const float ua1 = wa[0][hh][e0 + 1] * bfhi(pa[q]) + wa[1][hh][e0 + 1] * bfhi(ca[q]) + wa[2][hh][e0 + 1] * bfhi(na[q]) + wa[3][hh][e0 + 1];
;           const float ug0 = wg[0][hh][e0] * bflo(pg[q]) + wg[1][hh][e0] * bflo(cg[q]) + wg[2][hh][e0] * bflo(ng[q]) + wg[3][hh][e0];
;           const float ug1 = wg[0][hh][e0 + 1] * bfhi(pg[q]) + wg[1][hh][e0 + 1] * bfhi(cg[q]) + wg[2][hh][e0 + 1] * bfhi(ng[q]) + wg[3][hh][e0 + 1];
;           resw[q] = pk2(siluf(ug0) * ua0, siluf(ug1) * ua1);
;         }
;         u32x4 w; w.x = resw[0]; w.y = resw[1]; w.z = resw[2]; w.w = resw[3];
;         __builtin_nontemporal_store(w, (GAS u32x4*)(ea.out + (size_t)(m0 + r) * 2816 + ja0 + j8));
	v_mul_f32_e32 v142, v42, v112
	v_mul_f32_e32 v143, v43, v113
	v_mul_f32_e32 v144, v44, v114
	v_mul_f32_e32 v145, v45, v115
	v_fma_f32 v74, v34, v74, v142
	v_fma_f32 v75, v35, v75, v143
	v_fma_f32 v76, v36, v76, v144
	v_fma_f32 v77, v37, v77, v145
	v_fma_f32 v74, v50, v128, v74
	v_fma_f32 v75, v51, v129, v75
	v_fma_f32 v76, v52, v82, v76
	v_fma_f32 v77, v53, v83, v77
	v_add_f32_e32 v74, v58, v74
	v_add_f32_e32 v75, v59, v75
	v_add_f32_e32 v76, v60, v76
	v_add_f32_e32 v77, v61, v77
	v_mul_f32_e32 v142, v46, v116
	v_mul_f32_e32 v143, v47, v117
	v_mul_f32_e32 v144, v48, v118
	v_mul_f32_e32 v145, v49, v119
	v_fma_f32 v78, v38, v78, v142
	v_fma_f32 v79, v39, v79, v143
	v_fma_f32 v80, v40, v80, v144
	v_fma_f32 v81, v41, v81, v145
	v_fma_f32 v78, v54, v84, v78
	v_fma_f32 v79, v55, v85, v79
	v_fma_f32 v80, v56, v86, v80
	v_fma_f32 v81, v57, v87, v81
	v_add_f32_e32 v78, v62, v78
	v_add_f32_e32 v79, v63, v79
	v_add_f32_e32 v80, v64, v80
	v_add_f32_e32 v81, v65, v81
	v_mul_f32_e32 v138, 0xbfb8aa3b, v74
	v_mul_f32_e32 v139, 0xbfb8aa3b, v75
	v_mul_f32_e32 v140, 0xbfb8aa3b, v76
	v_mul_f32_e32 v141, 0xbfb8aa3b, v77
	v_exp_f32_e32 v138, v138
	v_exp_f32_e32 v139, v139
	v_exp_f32_e32 v140, v140
	v_exp_f32_e32 v141, v141
	v_add_f32_e32 v138, 1.0, v138
	v_add_f32_e32 v139, 1.0, v139
	v_add_f32_e32 v140, 1.0, v140
	v_add_f32_e32 v141, 1.0, v141
	v_rcp_f32_e32 v138, v138
	v_rcp_f32_e32 v139, v139
	v_rcp_f32_e32 v140, v140
	v_rcp_f32_e32 v141, v141
	v_mul_f32_e32 v74, v74, v138
	v_mul_f32_e32 v75, v75, v139
	v_mul_f32_e32 v76, v76, v140
	v_mul_f32_e32 v77, v77, v141
	v_mul_f32_e32 v66, v66, v74
	v_mul_f32_e32 v67, v67, v75
	v_mul_f32_e32 v68, v68, v76
	v_mul_f32_e32 v69, v69, v77
	v_mul_f32_e32 v138, 0xbfb8aa3b, v78
	v_mul_f32_e32 v139, 0xbfb8aa3b, v79
	v_mul_f32_e32 v140, 0xbfb8aa3b, v80
	v_mul_f32_e32 v141, 0xbfb8aa3b, v81
	v_exp_f32_e32 v138, v138
	v_exp_f32_e32 v139, v139
	v_exp_f32_e32 v140, v140
	v_exp_f32_e32 v141, v141
	v_add_f32_e32 v138, 1.0, v138
	v_add_f32_e32 v139, 1.0, v139
	v_add_f32_e32 v140, 1.0, v140
	v_add_f32_e32 v141, 1.0, v141
	v_rcp_f32_e32 v138, v138
	v_rcp_f32_e32 v139, v139
	v_rcp_f32_e32 v140, v140
	v_rcp_f32_e32 v141, v141
	v_mul_f32_e32 v78, v78, v138
	v_mul_f32_e32 v79, v79, v139
	v_mul_f32_e32 v80, v80, v140
	v_mul_f32_e32 v81, v81, v141
	v_mul_f32_e32 v70, v70, v78
	v_mul_f32_e32 v71, v71, v79
	v_mul_f32_e32 v72, v72, v80
	v_mul_f32_e32 v73, v73, v81
	v_cvt_pk_bf16_f32 v100, v66, v67
	v_cvt_pk_bf16_f32 v101, v68, v69
	v_cvt_pk_bf16_f32 v102, v70, v71
	v_cvt_pk_bf16_f32 v103, v72, v73
	s_mov_b64 vcc, exec
	s_orn2_b64 s[28:29], s[18:19], s[74:75]
	s_and_b64 exec, exec, s[28:29]
	global_store_dwordx4 v[88:89], v[100:103], off nt
	s_mov_b64 exec, vcc
	v_lshl_add_u64 v[94:95], v[88:89], 0, s[10:11]
	s_waitcnt lgkmcnt(4)
	v_lshlrev_b32_e32 v66, 16, v162
	v_and_b32_e32 v67, 0xffff0000, v162
	v_lshlrev_b32_e32 v68, 16, v163
	v_and_b32_e32 v69, 0xffff0000, v163
	v_lshlrev_b32_e32 v70, 16, v164
	v_and_b32_e32 v71, 0xffff0000, v164
	v_lshlrev_b32_e32 v72, 16, v165
	v_and_b32_e32 v73, 0xffff0000, v165
	v_lshlrev_b32_e32 v74, 16, v166
	v_and_b32_e32 v75, 0xffff0000, v166
	v_lshlrev_b32_e32 v76, 16, v167
	v_and_b32_e32 v77, 0xffff0000, v167
	v_lshlrev_b32_e32 v78, 16, v168
	v_and_b32_e32 v79, 0xffff0000, v168
	v_lshlrev_b32_e32 v80, 16, v169
	v_and_b32_e32 v81, 0xffff0000, v169
	v_mul_f32_e32 v138, v10, v120
	v_mul_f32_e32 v139, v11, v121
	v_mul_f32_e32 v140, v12, v122
	v_mul_f32_e32 v141, v13, v123
	v_fma_f32 v104, v2, v104, v138
	v_fma_f32 v105, v3, v105, v139
	v_fma_f32 v106, v4, v106, v140
	v_fma_f32 v107, v5, v107, v141
	v_fma_f32 v104, v18, v66, v104
	v_fma_f32 v105, v19, v67, v105
	v_fma_f32 v106, v20, v68, v106
	v_fma_f32 v107, v21, v69, v107
	v_add_f32_e32 v104, v26, v104
	v_add_f32_e32 v105, v27, v105
	v_add_f32_e32 v106, v28, v106
	v_add_f32_e32 v107, v29, v107
	v_mul_f32_e32 v138, v14, v124
	v_mul_f32_e32 v139, v15, v125
	v_mul_f32_e32 v140, v16, v126
	v_mul_f32_e32 v141, v17, v127
	v_fma_f32 v108, v6, v108, v138
	v_fma_f32 v109, v7, v109, v139
	v_fma_f32 v110, v8, v110, v140
	v_fma_f32 v111, v9, v111, v141
	v_fma_f32 v108, v22, v70, v108
	v_fma_f32 v109, v23, v71, v109
	v_fma_f32 v110, v24, v72, v110
	v_fma_f32 v111, v25, v73, v111
	v_add_f32_e32 v108, v30, v108
	v_add_f32_e32 v109, v31, v109
	v_add_f32_e32 v110, v32, v110
	v_add_f32_e32 v111, v33, v111
	v_mul_f32_e32 v142, v42, v128
	v_mul_f32_e32 v143, v43, v129
	v_mul_f32_e32 v144, v44, v82
	v_mul_f32_e32 v145, v45, v83
	v_fma_f32 v112, v34, v112, v142
	v_fma_f32 v113, v35, v113, v143
	v_fma_f32 v114, v36, v114, v144
	v_fma_f32 v115, v37, v115, v145
	v_fma_f32 v112, v50, v74, v112
	v_fma_f32 v113, v51, v75, v113
	v_fma_f32 v114, v52, v76, v114
	v_fma_f32 v115, v53, v77, v115
	v_add_f32_e32 v112, v58, v112
	v_add_f32_e32 v113, v59, v113
	v_add_f32_e32 v114, v60, v114
	v_add_f32_e32 v115, v61, v115
	v_mul_f32_e32 v142, v46, v84
	v_mul_f32_e32 v143, v47, v85
	v_mul_f32_e32 v144, v48, v86
	v_mul_f32_e32 v145, v49, v87
	v_fma_f32 v116, v38, v116, v142
	v_fma_f32 v117, v39, v117, v143
	v_fma_f32 v118, v40, v118, v144
	v_fma_f32 v119, v41, v119, v145
	v_fma_f32 v116, v54, v78, v116
	v_fma_f32 v117, v55, v79, v117
	v_fma_f32 v118, v56, v80, v118
	v_fma_f32 v119, v57, v81, v119
	v_add_f32_e32 v116, v62, v116
	v_add_f32_e32 v117, v63, v117
	v_add_f32_e32 v118, v64, v118
	v_add_f32_e32 v119, v65, v119
	v_mul_f32_e32 v138, 0xbfb8aa3b, v112
	v_mul_f32_e32 v139, 0xbfb8aa3b, v113
	v_mul_f32_e32 v140, 0xbfb8aa3b, v114
	v_mul_f32_e32 v141, 0xbfb8aa3b, v115
	v_exp_f32_e32 v138, v138
	v_exp_f32_e32 v139, v139
	v_exp_f32_e32 v140, v140
	v_exp_f32_e32 v141, v141
	v_add_f32_e32 v138, 1.0, v138
; #define GAS __attribute__((address_space(1)))
; DI unsigned pk2(float a, float b) { f32x2 v = {a, b}; bf2_t r = __builtin_convertvector(v, bf2_t); return __builtin_bit_cast(unsigned, r); }
; DI float bflo(unsigned w) { return __uint_as_float(w << 16); }
; DI float bfhi(unsigned w) { return __uint_as_float(w & 0xffff0000u); }
; DI float siluf(float v) { return v * __builtin_amdgcn_rcpf(1.f + __builtin_amdgcn_exp2f(-1.4426950408889634f * v)); }
;     ...
;         for (int q = 0; q < 4; ++q) {
;           const int hh = q >> 1, e0 = (q & 1) * 2;
;           const float ua0 = wa[0][hh][e0] * bflo(pa[q]) + wa[1][hh][e0] * bflo(ca[q]) + wa[2][hh][e0] * bflo(na[q]) + wa[3][hh][e0];
;           const float ua1 = wa[0][hh][e0 + 1] * bfhi(pa[q]) + wa[1][hh][e0 + 1] * bfhi(ca[q]) + wa[2][hh][e0 + 1] * bfhi(na[q]) + wa[3][hh][e0 + 1];
;           const float ug0 = wg[0][hh][e0] * bflo(pg[q]) + wg[1][hh][e0] * bflo(cg[q]) + wg[2][hh][e0] * bflo(ng[q]) + wg[3][hh][e0];
;           const float ug1 = wg[0][hh][e0 + 1] * bfhi(pg[q]) + wg[1][hh][e0 + 1] * bfhi(cg[q]) + wg[2][hh][e0 + 1] * bfhi(ng[q]) + wg[3][hh][e0 + 1];
;           resw[q] = pk2(siluf(ug0) * ua0, siluf(ug1) * ua1);
;         }
;         u32x4 w; w.x = resw[0]; w.y = resw[1]; w.z = resw[2]; w.w = resw[3];
;         __builtin_nontemporal_store(w, (GAS u32x4*)(ea.out + (size_t)(m0 + r) * 2816 + ja0 + j8));
	v_add_f32_e32 v139, 1.0, v139
	v_add_f32_e32 v140, 1.0, v140
	v_add_f32_e32 v141, 1.0, v141
	v_rcp_f32_e32 v138, v138
	v_rcp_f32_e32 v139, v139
	v_rcp_f32_e32 v140, v140
	v_rcp_f32_e32 v141, v141
	v_mul_f32_e32 v112, v112, v138
	v_mul_f32_e32 v113, v113, v139
	v_mul_f32_e32 v114, v114, v140
	v_mul_f32_e32 v115, v115, v141
	v_mul_f32_e32 v104, v104, v112
	v_mul_f32_e32 v105, v105, v113
	v_mul_f32_e32 v106, v106, v114
	v_mul_f32_e32 v107, v107, v115
	v_mul_f32_e32 v138, 0xbfb8aa3b, v116
	v_mul_f32_e32 v139, 0xbfb8aa3b, v117
	v_mul_f32_e32 v140, 0xbfb8aa3b, v118
	v_mul_f32_e32 v141, 0xbfb8aa3b, v119
	v_exp_f32_e32 v138, v138
	v_exp_f32_e32 v139, v139
	v_exp_f32_e32 v140, v140
	v_exp_f32_e32 v141, v141
	v_add_f32_e32 v138, 1.0, v138
	v_add_f32_e32 v139, 1.0, v139
	v_add_f32_e32 v140, 1.0, v140
	v_add_f32_e32 v141, 1.0, v141
	v_rcp_f32_e32 v138, v138
	v_rcp_f32_e32 v139, v139
	v_rcp_f32_e32 v140, v140
	v_rcp_f32_e32 v141, v141
	v_mul_f32_e32 v116, v116, v138
	v_mul_f32_e32 v117, v117, v139
	v_mul_f32_e32 v118, v118, v140
	v_mul_f32_e32 v119, v119, v141
	v_mul_f32_e32 v108, v108, v116
	v_mul_f32_e32 v109, v109, v117
	v_mul_f32_e32 v110, v110, v118
	v_mul_f32_e32 v111, v111, v119
	v_cvt_pk_bf16_f32 v100, v104, v105
	v_cvt_pk_bf16_f32 v101, v106, v107
	v_cvt_pk_bf16_f32 v102, v108, v109
	v_cvt_pk_bf16_f32 v103, v110, v111
	global_store_dwordx4 v[94:95], v[100:103], off nt
	v_lshl_add_u64 v[88:89], v[94:95], 0, s[10:11]
	s_waitcnt lgkmcnt(2)
	v_lshlrev_b32_e32 v104, 16, v170
	v_and_b32_e32 v105, 0xffff0000, v170
	v_lshlrev_b32_e32 v106, 16, v171
	v_and_b32_e32 v107, 0xffff0000, v171
	v_lshlrev_b32_e32 v108, 16, v172
	v_and_b32_e32 v109, 0xffff0000, v172
	v_lshlrev_b32_e32 v110, 16, v173
	v_and_b32_e32 v111, 0xffff0000, v173
	v_lshlrev_b32_e32 v112, 16, v174
	v_and_b32_e32 v113, 0xffff0000, v174
	v_lshlrev_b32_e32 v114, 16, v175
	v_and_b32_e32 v115, 0xffff0000, v175
	v_lshlrev_b32_e32 v116, 16, v176
	v_and_b32_e32 v117, 0xffff0000, v176
	v_lshlrev_b32_e32 v118, 16, v177
	v_and_b32_e32 v119, 0xffff0000, v177
	v_mul_f32_e32 v138, v10, v66
	v_mul_f32_e32 v139, v11, v67
	v_mul_f32_e32 v140, v12, v68
	v_mul_f32_e32 v141, v13, v69
	v_fma_f32 v120, v2, v120, v138
	v_fma_f32 v121, v3, v121, v139
	v_fma_f32 v122, v4, v122, v140
	v_fma_f32 v123, v5, v123, v141
	v_fma_f32 v120, v18, v104, v120
	v_fma_f32 v121, v19, v105, v121
	v_fma_f32 v122, v20, v106, v122
	v_fma_f32 v123, v21, v107, v123
	v_add_f32_e32 v120, v26, v120
	v_add_f32_e32 v121, v27, v121
	v_add_f32_e32 v122, v28, v122
	v_add_f32_e32 v123, v29, v123
	v_mul_f32_e32 v138, v14, v70
	v_mul_f32_e32 v139, v15, v71
	v_mul_f32_e32 v140, v16, v72
	v_mul_f32_e32 v141, v17, v73
	v_fma_f32 v124, v6, v124, v138
	v_fma_f32 v125, v7, v125, v139
	v_fma_f32 v126, v8, v126, v140
	v_fma_f32 v127, v9, v127, v141
	v_fma_f32 v124, v22, v108, v124
	v_fma_f32 v125, v23, v109, v125
	v_fma_f32 v126, v24, v110, v126
	v_fma_f32 v127, v25, v111, v127
	v_add_f32_e32 v124, v30, v124
	v_add_f32_e32 v125, v31, v125
	v_add_f32_e32 v126, v32, v126
	v_add_f32_e32 v127, v33, v127
	v_mul_f32_e32 v142, v42, v74
	v_mul_f32_e32 v143, v43, v75
	v_mul_f32_e32 v144, v44, v76
	v_mul_f32_e32 v145, v45, v77
	v_fma_f32 v128, v34, v128, v142
	v_fma_f32 v129, v35, v129, v143
	v_fma_f32 v82, v36, v82, v144
	v_fma_f32 v83, v37, v83, v145
	v_fma_f32 v128, v50, v112, v128
	v_fma_f32 v129, v51, v113, v129
	v_fma_f32 v82, v52, v114, v82
	v_fma_f32 v83, v53, v115, v83
	v_add_f32_e32 v128, v58, v128
	v_add_f32_e32 v129, v59, v129
	v_add_f32_e32 v82, v60, v82
	v_add_f32_e32 v83, v61, v83
	v_mul_f32_e32 v142, v46, v78
	v_mul_f32_e32 v143, v47, v79
	v_mul_f32_e32 v144, v48, v80
	v_mul_f32_e32 v145, v49, v81
	v_fma_f32 v84, v38, v84, v142
	v_fma_f32 v85, v39, v85, v143
	v_fma_f32 v86, v40, v86, v144
	v_fma_f32 v87, v41, v87, v145
	v_fma_f32 v84, v54, v116, v84
	v_fma_f32 v85, v55, v117, v85
	v_fma_f32 v86, v56, v118, v86
	v_fma_f32 v87, v57, v119, v87
	v_add_f32_e32 v84, v62, v84
	v_add_f32_e32 v85, v63, v85
	v_add_f32_e32 v86, v64, v86
	v_add_f32_e32 v87, v65, v87
	v_mul_f32_e32 v138, 0xbfb8aa3b, v128
	v_mul_f32_e32 v139, 0xbfb8aa3b, v129
	v_mul_f32_e32 v140, 0xbfb8aa3b, v82
	v_mul_f32_e32 v141, 0xbfb8aa3b, v83
	v_exp_f32_e32 v138, v138
	v_exp_f32_e32 v139, v139
	v_exp_f32_e32 v140, v140
	v_exp_f32_e32 v141, v141
	v_add_f32_e32 v138, 1.0, v138
	v_add_f32_e32 v139, 1.0, v139
	v_add_f32_e32 v140, 1.0, v140
	v_add_f32_e32 v141, 1.0, v141
	v_rcp_f32_e32 v138, v138
	v_rcp_f32_e32 v139, v139
	v_rcp_f32_e32 v140, v140
	v_rcp_f32_e32 v141, v141
	v_mul_f32_e32 v128, v128, v138
	v_mul_f32_e32 v129, v129, v139
	v_mul_f32_e32 v82, v82, v140
	v_mul_f32_e32 v83, v83, v141
	v_mul_f32_e32 v120, v120, v128
	v_mul_f32_e32 v121, v121, v129
	v_mul_f32_e32 v122, v122, v82
	v_mul_f32_e32 v123, v123, v83
	v_mul_f32_e32 v138, 0xbfb8aa3b, v84
	v_mul_f32_e32 v139, 0xbfb8aa3b, v85
	v_mul_f32_e32 v140, 0xbfb8aa3b, v86
	v_mul_f32_e32 v141, 0xbfb8aa3b, v87
	v_exp_f32_e32 v138, v138
	v_exp_f32_e32 v139, v139
	v_exp_f32_e32 v140, v140
	v_exp_f32_e32 v141, v141
	v_add_f32_e32 v138, 1.0, v138
	v_add_f32_e32 v139, 1.0, v139
	v_add_f32_e32 v140, 1.0, v140
	v_add_f32_e32 v141, 1.0, v141
	v_rcp_f32_e32 v138, v138
	v_rcp_f32_e32 v139, v139
	v_rcp_f32_e32 v140, v140
	v_rcp_f32_e32 v141, v141
	v_mul_f32_e32 v84, v84, v138
	v_mul_f32_e32 v85, v85, v139
	v_mul_f32_e32 v86, v86, v140
	v_mul_f32_e32 v87, v87, v141
	v_mul_f32_e32 v124, v124, v84
	v_mul_f32_e32 v125, v125, v85
	v_mul_f32_e32 v126, v126, v86
	v_mul_f32_e32 v127, v127, v87
	v_cvt_pk_bf16_f32 v100, v120, v121
	v_cvt_pk_bf16_f32 v101, v122, v123
	v_cvt_pk_bf16_f32 v102, v124, v125
	v_cvt_pk_bf16_f32 v103, v126, v127
	global_store_dwordx4 v[88:89], v[100:103], off nt
	v_lshl_add_u64 v[94:95], v[88:89], 0, s[10:11]
	s_waitcnt lgkmcnt(0)
	s_and_b64 s[28:29], exec, s[40:41]
	s_cbranch_scc0 .Lmy_e1_bot
	s_mov_b64 vcc, exec
	s_mov_b64 exec, s[28:29]
	v_mov_b32_e32 v178, 0
	v_mov_b32_e32 v179, 0
	v_mov_b32_e32 v180, 0
	v_mov_b32_e32 v181, 0
	v_mov_b32_e32 v182, 0
	v_mov_b32_e32 v183, 0
	v_mov_b32_e32 v184, 0
	v_mov_b32_e32 v185, 0
	s_mov_b64 exec, vcc
; #define GAS __attribute__((address_space(1)))
; DI unsigned pk2(float a, float b) { f32x2 v = {a, b}; bf2_t r = __builtin_convertvector(v, bf2_t); return __builtin_bit_cast(unsigned, r); }
; DI float bflo(unsigned w) { return __uint_as_float(w << 16); }
; DI float bfhi(unsigned w) { return __uint_as_float(w & 0xffff0000u); }
; DI float siluf(float v) { return v * __builtin_amdgcn_rcpf(1.f + __builtin_amdgcn_exp2f(-1.4426950408889634f * v)); }
;     ...
;         for (int q = 0; q < 4; ++q) {
;           const int hh = q >> 1, e0 = (q & 1) * 2;
;           const float ua0 = wa[0][hh][e0] * bflo(pa[q]) + wa[1][hh][e0] * bflo(ca[q]) + wa[2][hh][e0] * bflo(na[q]) + wa[3][hh][e0];
;           const float ua1 = wa[0][hh][e0 + 1] * bfhi(pa[q]) + wa[1][hh][e0 + 1] * bfhi(ca[q]) + wa[2][hh][e0 + 1] * bfhi(na[q]) + wa[3][hh][e0 + 1];
;           const float ug0 = wg[0][hh][e0] * bflo(pg[q]) + wg[1][hh][e0] * bflo(cg[q]) + wg[2][hh][e0] * bflo(ng[q]) + wg[3][hh][e0];
;           const float ug1 = wg[0][hh][e0 + 1] * bfhi(pg[q]) + wg[1][hh][e0 + 1] * bfhi(cg[q]) + wg[2][hh][e0 + 1] * bfhi(ng[q]) + wg[3][hh][e0 + 1];
;           resw[q] = pk2(siluf(ug0) * ua0, siluf(ug1) * ua1);
;         }
;         u32x4 w; w.x = resw[0]; w.y = resw[1]; w.z = resw[2]; w.w = resw[3];
;         __builtin_nontemporal_store(w, (GAS u32x4*)(ea.out + (size_t)(m0 + r) * 2816 + ja0 + j8));
.Lmy_e1_bot:
	v_lshlrev_b32_e32 v120, 16, v178
	v_and_b32_e32 v121, 0xffff0000, v178
	v_lshlrev_b32_e32 v122, 16, v179
	v_and_b32_e32 v123, 0xffff0000, v179
	v_lshlrev_b32_e32 v124, 16, v180
	v_and_b32_e32 v125, 0xffff0000, v180
	v_lshlrev_b32_e32 v126, 16, v181
	v_and_b32_e32 v127, 0xffff0000, v181
	v_lshlrev_b32_e32 v128, 16, v182
	v_and_b32_e32 v129, 0xffff0000, v182
	v_lshlrev_b32_e32 v82, 16, v183
	v_and_b32_e32 v83, 0xffff0000, v183
	v_lshlrev_b32_e32 v84, 16, v184
	v_and_b32_e32 v85, 0xffff0000, v184
	v_lshlrev_b32_e32 v86, 16, v185
	v_and_b32_e32 v87, 0xffff0000, v185
	v_mul_f32_e32 v138, v10, v104
	v_mul_f32_e32 v139, v11, v105
	v_mul_f32_e32 v140, v12, v106
	v_mul_f32_e32 v141, v13, v107
	v_fma_f32 v66, v2, v66, v138
	v_fma_f32 v67, v3, v67, v139
	v_fma_f32 v68, v4, v68, v140
	v_fma_f32 v69, v5, v69, v141
	v_fma_f32 v66, v18, v120, v66
	v_fma_f32 v67, v19, v121, v67
	v_fma_f32 v68, v20, v122, v68
	v_fma_f32 v69, v21, v123, v69
	v_add_f32_e32 v66, v26, v66
	v_add_f32_e32 v67, v27, v67
	v_add_f32_e32 v68, v28, v68
	v_add_f32_e32 v69, v29, v69
	v_mul_f32_e32 v138, v14, v108
	v_mul_f32_e32 v139, v15, v109
	v_mul_f32_e32 v140, v16, v110
	v_mul_f32_e32 v141, v17, v111
	v_fma_f32 v70, v6, v70, v138
	v_fma_f32 v71, v7, v71, v139
	v_fma_f32 v72, v8, v72, v140
	v_fma_f32 v73, v9, v73, v141
	v_fma_f32 v70, v22, v124, v70
	v_fma_f32 v71, v23, v125, v71
	v_fma_f32 v72, v24, v126, v72
	v_fma_f32 v73, v25, v127, v73
	v_add_f32_e32 v70, v30, v70
	v_add_f32_e32 v71, v31, v71
	v_add_f32_e32 v72, v32, v72
	v_add_f32_e32 v73, v33, v73
	v_mul_f32_e32 v142, v42, v112
	v_mul_f32_e32 v143, v43, v113
	v_mul_f32_e32 v144, v44, v114
	v_mul_f32_e32 v145, v45, v115
	v_fma_f32 v74, v34, v74, v142
	v_fma_f32 v75, v35, v75, v143
	v_fma_f32 v76, v36, v76, v144
	v_fma_f32 v77, v37, v77, v145
	v_fma_f32 v74, v50, v128, v74
	v_fma_f32 v75, v51, v129, v75
	v_fma_f32 v76, v52, v82, v76
	v_fma_f32 v77, v53, v83, v77
	v_add_f32_e32 v74, v58, v74
	v_add_f32_e32 v75, v59, v75
	v_add_f32_e32 v76, v60, v76
	v_add_f32_e32 v77, v61, v77
	v_mul_f32_e32 v142, v46, v116
	v_mul_f32_e32 v143, v47, v117
	v_mul_f32_e32 v144, v48, v118
	v_mul_f32_e32 v145, v49, v119
	v_fma_f32 v78, v38, v78, v142
	v_fma_f32 v79, v39, v79, v143
	v_fma_f32 v80, v40, v80, v144
	v_fma_f32 v81, v41, v81, v145
	v_fma_f32 v78, v54, v84, v78
	v_fma_f32 v79, v55, v85, v79
	v_fma_f32 v80, v56, v86, v80
	v_fma_f32 v81, v57, v87, v81
	v_add_f32_e32 v78, v62, v78
	v_add_f32_e32 v79, v63, v79
	v_add_f32_e32 v80, v64, v80
	v_add_f32_e32 v81, v65, v81
	v_mul_f32_e32 v138, 0xbfb8aa3b, v74
	v_mul_f32_e32 v139, 0xbfb8aa3b, v75
	v_mul_f32_e32 v140, 0xbfb8aa3b, v76
	v_mul_f32_e32 v141, 0xbfb8aa3b, v77
	v_exp_f32_e32 v138, v138
	v_exp_f32_e32 v139, v139
	v_exp_f32_e32 v140, v140
	v_exp_f32_e32 v141, v141
	v_add_f32_e32 v138, 1.0, v138
	v_add_f32_e32 v139, 1.0, v139
	v_add_f32_e32 v140, 1.0, v140
	v_add_f32_e32 v141, 1.0, v141
	v_rcp_f32_e32 v138, v138
	v_rcp_f32_e32 v139, v139
	v_rcp_f32_e32 v140, v140
	v_rcp_f32_e32 v141, v141
	v_mul_f32_e32 v74, v74, v138
	v_mul_f32_e32 v75, v75, v139
	v_mul_f32_e32 v76, v76, v140
	v_mul_f32_e32 v77, v77, v141
	v_mul_f32_e32 v66, v66, v74
	v_mul_f32_e32 v67, v67, v75
	v_mul_f32_e32 v68, v68, v76
	v_mul_f32_e32 v69, v69, v77
	v_mul_f32_e32 v138, 0xbfb8aa3b, v78
	v_mul_f32_e32 v139, 0xbfb8aa3b, v79
	v_mul_f32_e32 v140, 0xbfb8aa3b, v80
	v_mul_f32_e32 v141, 0xbfb8aa3b, v81
	v_exp_f32_e32 v138, v138
	v_exp_f32_e32 v139, v139
	v_exp_f32_e32 v140, v140
	v_exp_f32_e32 v141, v141
	v_add_f32_e32 v138, 1.0, v138
	v_add_f32_e32 v139, 1.0, v139
	v_add_f32_e32 v140, 1.0, v140
	v_add_f32_e32 v141, 1.0, v141
	v_rcp_f32_e32 v138, v138
	v_rcp_f32_e32 v139, v139
	v_rcp_f32_e32 v140, v140
	v_rcp_f32_e32 v141, v141
	v_mul_f32_e32 v78, v78, v138
	v_mul_f32_e32 v79, v79, v139
	v_mul_f32_e32 v80, v80, v140
	v_mul_f32_e32 v81, v81, v141
	v_mul_f32_e32 v70, v70, v78
	v_mul_f32_e32 v71, v71, v79
	v_mul_f32_e32 v72, v72, v80
	v_mul_f32_e32 v73, v73, v81
	v_cvt_pk_bf16_f32 v100, v66, v67
	v_cvt_pk_bf16_f32 v101, v68, v69
	v_cvt_pk_bf16_f32 v102, v70, v71
	v_cvt_pk_bf16_f32 v103, v72, v73
	s_mov_b64 vcc, exec
	s_orn2_b64 s[28:29], s[20:21], s[40:41]
	s_and_b64 exec, exec, s[28:29]
	global_store_dwordx4 v[94:95], v[100:103], off nt
	s_mov_b64 exec, vcc
	s_branch .LBB0_274
